# attention GQA+MLA loops: K-fragment LDS reads issued up-front into free VGPRs, untied p1 init, V^T second half hoisted
# speedup vs baseline: 1.0086x; 1.0086x over previous
.LBB0_294:
	s_mul_i32 s55, s33, 0x5000
	s_add_i32 s0, s55, 0
	v_add_u32_e32 v68, s0, v122
	s_barrier
	v_add_u32_e32 v48, v68, v125
	v_add_u32_e32 v69, v68, v126
	v_add_u32_e32 v70, v68, v127
	v_add_u32_e32 v68, v68, v128
	v_add_u32_e32 v130, s0, v129
	ds_read_b128 v[192:195], v48
	ds_read_b128 v[196:199], v69
	ds_read_b128 v[200:203], v70
	ds_read_b128 v[208:211], v68
	ds_read_b128 v[98:101], v48 offset:4096
	ds_read_b128 v[102:105], v69 offset:4096
	ds_read_b128 v[106:109], v70 offset:4096
	ds_read_b128 v[132:135], v68 offset:4096
	s_waitcnt lgkmcnt(7)
	v_mfma_f32_32x32x16_bf16 v[48:63], v[192:195], v[82:85], v[32:47]
	s_waitcnt lgkmcnt(6)
	v_mfma_f32_32x32x16_bf16 v[48:63], v[196:199], v[86:89], v[48:63]
	s_waitcnt lgkmcnt(5)
	v_mfma_f32_32x32x16_bf16 v[48:63], v[200:203], v[90:93], v[48:63]
	s_waitcnt lgkmcnt(4)
	v_mfma_f32_32x32x16_bf16 v[48:63], v[208:211], v[94:97], v[48:63]
	s_waitcnt lgkmcnt(3)
	v_mfma_f32_32x32x16_bf16 v[64:79], v[98:101], v[82:85], v[32:47]
	s_waitcnt lgkmcnt(2)
	v_mfma_f32_32x32x16_bf16 v[64:79], v[102:105], v[86:89], v[64:79]
	ds_read_b64_tr_b16 v[110:111], v130 offset:12288
	ds_read_b64_tr_b16 v[112:113], v130 offset:12800
	ds_read_b64_tr_b16 v[102:103], v130 offset:13312
	ds_read_b64_tr_b16 v[104:105], v130 offset:13824
	s_waitcnt lgkmcnt(5)
	v_mfma_f32_32x32x16_bf16 v[64:79], v[106:109], v[90:93], v[64:79]
	s_nop 1
	v_max_f32_e32 v98, v49, v49
	v_max_f32_e32 v99, v48, v48
	v_max_f32_e32 v98, v99, v98
	v_max3_f32 v98, v98, v50, v51
	v_max3_f32 v98, v98, v52, v53
	v_max3_f32 v98, v98, v54, v55
	v_max3_f32 v98, v98, v56, v57
	s_waitcnt lgkmcnt(4)
	v_mfma_f32_32x32x16_bf16 v[64:79], v[132:135], v[94:97], v[64:79]
	v_max3_f32 v98, v98, v58, v59
	v_max3_f32 v98, v98, v60, v61
	v_max3_f32 v98, v98, v62, v63
	s_nop 8
	v_max3_f32 v98, v98, v64, v65
	v_max3_f32 v98, v98, v66, v67
	v_max3_f32 v98, v98, v68, v69
	v_max3_f32 v98, v98, v70, v71
	v_max3_f32 v98, v98, v72, v73
	v_max3_f32 v98, v98, v74, v75
	v_max3_f32 v98, v98, v76, v77
	v_max3_f32 v131, v98, v78, v79
	ds_bpermute_b32 v132, v219, v131
	ds_read_b64_tr_b16 v[106:107], v130 offset:14336
	ds_read_b64_tr_b16 v[108:109], v130 offset:14848
	ds_read_b64_tr_b16 v[98:99], v130 offset:15360
	ds_read_b64_tr_b16 v[100:101], v130 offset:15872
	s_waitcnt lgkmcnt(4)
	ds_read_b64_tr_b16 v[212:213], v130 offset:16384
	ds_read_b64_tr_b16 v[214:215], v130 offset:16896
	ds_read_b64_tr_b16 v[224:225], v130 offset:17408
	ds_read_b64_tr_b16 v[226:227], v130 offset:17920
	ds_read_b64_tr_b16 v[228:229], v130 offset:18432
	ds_read_b64_tr_b16 v[230:231], v130 offset:18944
	ds_read_b64_tr_b16 v[232:233], v130 offset:19456
	ds_read_b64_tr_b16 v[234:235], v130 offset:19968
	v_max_f32_e32 v132, v132, v132
	v_max_f32_e32 v131, v131, v132
	v_cmp_lt_f32_e32 vcc, s72, v131
	s_cbranch_vccz .LBB0_298
	v_max_f32_e32 v32, v131, v131
	v_max_f32_e32 v32, 0, v32
	v_exp_f32_e64 v33, -v32
	s_and_saveexec_b64 s[44:45], s[40:41]
	ds_write_b32 v123, v33
	s_or_b64 exec, exec, s[44:45]
	s_waitcnt lgkmcnt(0)
	ds_read_b128 v[34:37], v124
	ds_read_b128 v[38:41], v124 offset:32
	ds_read_b128 v[42:45], v124 offset:64
	ds_read_b128 v[132:135], v124 offset:96
	v_pk_add_f32 v[48:49], v[48:49], v[32:33] op_sel_hi:[1,0] neg_lo:[0,1] neg_hi:[0,1]
	v_pk_add_f32 v[64:65], v[64:65], v[32:33] op_sel_hi:[1,0] neg_lo:[0,1] neg_hi:[0,1]
	v_pk_add_f32 v[50:51], v[50:51], v[32:33] op_sel_hi:[1,0] neg_lo:[0,1] neg_hi:[0,1]
	v_pk_add_f32 v[66:67], v[66:67], v[32:33] op_sel_hi:[1,0] neg_lo:[0,1] neg_hi:[0,1]
	v_pk_add_f32 v[52:53], v[52:53], v[32:33] op_sel_hi:[1,0] neg_lo:[0,1] neg_hi:[0,1]
	v_pk_add_f32 v[68:69], v[68:69], v[32:33] op_sel_hi:[1,0] neg_lo:[0,1] neg_hi:[0,1]
	v_pk_add_f32 v[54:55], v[54:55], v[32:33] op_sel_hi:[1,0] neg_lo:[0,1] neg_hi:[0,1]
	v_pk_add_f32 v[70:71], v[70:71], v[32:33] op_sel_hi:[1,0] neg_lo:[0,1] neg_hi:[0,1]
	v_pk_add_f32 v[56:57], v[56:57], v[32:33] op_sel_hi:[1,0] neg_lo:[0,1] neg_hi:[0,1]
	v_pk_add_f32 v[72:73], v[72:73], v[32:33] op_sel_hi:[1,0] neg_lo:[0,1] neg_hi:[0,1]
	v_pk_add_f32 v[58:59], v[58:59], v[32:33] op_sel_hi:[1,0] neg_lo:[0,1] neg_hi:[0,1]
	v_pk_add_f32 v[74:75], v[74:75], v[32:33] op_sel_hi:[1,0] neg_lo:[0,1] neg_hi:[0,1]
	v_pk_add_f32 v[60:61], v[60:61], v[32:33] op_sel_hi:[1,0] neg_lo:[0,1] neg_hi:[0,1]
	v_pk_add_f32 v[76:77], v[76:77], v[32:33] op_sel_hi:[1,0] neg_lo:[0,1] neg_hi:[0,1]
	v_pk_add_f32 v[62:63], v[62:63], v[32:33] op_sel_hi:[1,0] neg_lo:[0,1] neg_hi:[0,1]
	v_pk_add_f32 v[78:79], v[78:79], v[32:33] op_sel_hi:[1,0] neg_lo:[0,1] neg_hi:[0,1]
	v_pk_add_f32 v[136:137], v[114:115], v[32:33]
	v_pk_mul_f32 v[32:33], v[114:115], v[32:33]
	s_waitcnt lgkmcnt(3)
	v_pk_mul_f32 v[0:1], v[0:1], v[34:35]
	v_mov_b32_e32 v137, v33
	v_pk_add_f32 v[46:47], v[136:137], 0 neg_lo:[1,1] neg_hi:[1,1]
	v_pk_mul_f32 v[2:3], v[2:3], v[36:37]
	s_waitcnt lgkmcnt(2)
	v_pk_mul_f32 v[4:5], v[4:5], v[38:39]
	v_pk_mul_f32 v[6:7], v[6:7], v[40:41]
	s_waitcnt lgkmcnt(1)
	v_pk_mul_f32 v[8:9], v[8:9], v[42:43]
	v_pk_mul_f32 v[10:11], v[10:11], v[44:45]
	s_waitcnt lgkmcnt(0)
	v_pk_mul_f32 v[12:13], v[12:13], v[132:133]
	v_pk_mul_f32 v[14:15], v[14:15], v[134:135]
	v_pk_mul_f32 v[30:31], v[30:31], v[134:135]
	v_pk_mul_f32 v[26:27], v[26:27], v[44:45]
	v_pk_mul_f32 v[22:23], v[22:23], v[40:41]
	v_pk_mul_f32 v[18:19], v[18:19], v[36:37]
	v_pk_mul_f32 v[28:29], v[28:29], v[132:133]
	v_pk_mul_f32 v[24:25], v[24:25], v[42:43]
	v_pk_mul_f32 v[20:21], v[20:21], v[38:39]
	v_pk_mul_f32 v[16:17], v[16:17], v[34:35]
	v_mov_b32_e32 v47, v46
	v_mov_b32_e32 v45, v46
	v_mov_b32_e32 v44, v46
	v_mov_b32_e32 v43, v46
	v_mov_b32_e32 v42, v46
	v_mov_b32_e32 v41, v46
	v_mov_b32_e32 v40, v46
	v_mov_b32_e32 v39, v46
	v_mov_b32_e32 v38, v46
	v_mov_b32_e32 v37, v46
	v_mov_b32_e32 v36, v46
	v_mov_b32_e32 v35, v46
	v_mov_b32_e32 v34, v46
	v_mov_b32_e32 v33, v46
	v_mov_b32_e32 v32, v46
	v_mov_b64_e32 v[114:115], v[136:137]

.LBB0_300:
	v_exp_f32_e32 v48, v48
	v_exp_f32_e32 v64, v64
	v_exp_f32_e32 v49, v49
	v_exp_f32_e32 v65, v65
	v_exp_f32_e32 v50, v50
	v_exp_f32_e32 v66, v66
	v_exp_f32_e32 v51, v51
	v_exp_f32_e32 v67, v67
	v_add_f32_e32 v131, v64, v48
	v_exp_f32_e32 v52, v52
	v_exp_f32_e32 v68, v68
	v_add_f32_e32 v131, 0, v131
	v_add_f32_e32 v132, v65, v49
	v_exp_f32_e32 v53, v53
	v_exp_f32_e32 v69, v69
	v_add_f32_e32 v131, v132, v131
	v_add_f32_e32 v132, v66, v50
	v_exp_f32_e32 v54, v54
	v_exp_f32_e32 v70, v70
	v_add_f32_e32 v131, v132, v131
	v_add_f32_e32 v132, v67, v51
	v_exp_f32_e32 v55, v55
	v_exp_f32_e32 v71, v71
	v_add_f32_e32 v131, v132, v131
	v_add_f32_e32 v132, v68, v52
	v_exp_f32_e32 v56, v56
	v_exp_f32_e32 v72, v72
	v_add_f32_e32 v131, v132, v131
	v_add_f32_e32 v132, v69, v53
	v_exp_f32_e32 v57, v57
	v_exp_f32_e32 v73, v73
	v_add_f32_e32 v131, v132, v131
	v_add_f32_e32 v132, v70, v54
	v_exp_f32_e32 v58, v58
	v_exp_f32_e32 v74, v74
	v_add_f32_e32 v131, v132, v131
	v_add_f32_e32 v132, v71, v55
	v_exp_f32_e32 v59, v59
	v_exp_f32_e32 v75, v75
	v_add_f32_e32 v131, v132, v131
	v_add_f32_e32 v132, v72, v56
	v_add_f32_e32 v131, v132, v131
	v_add_f32_e32 v132, v73, v57
	v_add_f32_e32 v131, v132, v131
	v_add_f32_e32 v132, v74, v58
	v_add_f32_e32 v131, v132, v131
	v_add_f32_e32 v132, v75, v59
	v_add_f32_e32 v131, v132, v131
	v_exp_f32_e32 v132, v60
	v_exp_f32_e32 v76, v76
	v_exp_f32_e32 v77, v77
	v_exp_f32_e32 v133, v62
	v_exp_f32_e32 v78, v78
	v_add_f32_e32 v60, v76, v132
	v_add_f32_e32 v60, v60, v131
	v_exp_f32_e32 v131, v61
	v_exp_f32_e32 v134, v63
	v_exp_f32_e32 v79, v79
	v_cvt_pk_bf16_f32 v62, v52, v53
	v_add_f32_e32 v61, v77, v131
	v_add_f32_e32 v60, v61, v60
	v_add_f32_e32 v61, v78, v133
	v_add_f32_e32 v60, v61, v60
	v_add_f32_e32 v61, v79, v134
	v_add_f32_e32 v60, v61, v60
	v_add_f32_e32 v115, v115, v60
	v_cvt_pk_bf16_f32 v60, v48, v49
	v_cvt_pk_bf16_f32 v61, v50, v51
	v_cvt_pk_bf16_f32 v63, v54, v55
	v_cvt_pk_bf16_f32 v52, v64, v65
	v_cvt_pk_bf16_f32 v53, v66, v67
	v_cvt_pk_bf16_f32 v54, v68, v69
	v_cvt_pk_bf16_f32 v55, v70, v71
	v_cvt_pk_bf16_f32 v48, v72, v73
	v_cvt_pk_bf16_f32 v49, v74, v75
	v_cvt_pk_bf16_f32 v50, v76, v77
	v_cvt_pk_bf16_f32 v51, v78, v79
	s_waitcnt lgkmcnt(0)
	v_mfma_f32_32x32x16_bf16 v[0:15], v[60:63], v[110:113], v[0:15]
	v_cvt_pk_bf16_f32 v56, v56, v57
	v_cvt_pk_bf16_f32 v57, v58, v59
	v_cvt_pk_bf16_f32 v58, v132, v131
	v_cvt_pk_bf16_f32 v59, v133, v134
	s_add_i32 s0, s33, 1
	s_cmp_lg_u32 s33, 2
	v_mfma_f32_32x32x16_bf16 v[16:31], v[60:63], v[212:215], v[16:31]
	s_cselect_b32 s33, s0, 0
	v_lshl_add_u64 v[116:117], v[116:117], 0, s[66:67]
	v_lshl_add_u64 v[118:119], v[118:119], 0, s[66:67]
	s_cmp_eq_u32 s37, s50
	v_mfma_f32_32x32x16_bf16 v[0:15], v[56:59], v[102:105], v[0:15]
	v_mfma_f32_32x32x16_bf16 v[16:31], v[56:59], v[224:227], v[16:31]
	v_mfma_f32_32x32x16_bf16 v[0:15], v[52:55], v[106:109], v[0:15]
	v_mfma_f32_32x32x16_bf16 v[16:31], v[52:55], v[228:231], v[16:31]
	v_mfma_f32_32x32x16_bf16 v[0:15], v[48:51], v[98:101], v[0:15]
	v_mfma_f32_32x32x16_bf16 v[16:31], v[48:51], v[232:235], v[16:31]
	s_cbranch_scc0 .LBB0_290
	ds_bpermute_b32 v32, v219, v115
	s_nop 0
	v_cmp_eq_u32_e32 vcc, 0, v120
	s_and_saveexec_b64 s[40:41], vcc
	s_cbranch_execz .LBB0_303
	s_waitcnt lgkmcnt(0)
	v_add_f32_e32 v32, v115, v32
	v_div_scale_f32 v33, s[36:37], v32, v32, 1.0
	v_rcp_f32_e32 v34, v33
	v_div_scale_f32 v35, vcc, 1.0, v32, 1.0
	v_fma_f32 v36, -v33, v34, 1.0
	v_fmac_f32_e32 v34, v36, v34
	v_mul_f32_e32 v36, v35, v34
	v_fma_f32 v37, -v33, v36, v35
	v_fmac_f32_e32 v36, v37, v34
	v_fma_f32 v33, -v33, v36, v35
	v_div_fmas_f32 v33, v33, v34, v36
	v_div_fixup_f32 v32, v33, v32, 1.0
	v_lshl_add_u32 v33, v121, 2, s6
	ds_write_b32 v33, v32

.LBB0_345:
	s_mul_i32 s54, s11, 0x5000
	s_add_i32 s0, s54, 0
	v_add_u32_e32 v68, s0, v132
	s_barrier
	v_add_u32_e32 v69, v68, v136
	v_add_u32_e32 v110, v68, v137
	v_add_u32_e32 v111, v68, v138
	v_add_u32_e32 v112, v68, v139
	v_add_u32_e32 v68, s0, v133
	v_add_u32_e32 v113, v68, v140
	v_add_u32_e32 v118, v68, v141
	v_add_u32_e32 v143, s0, v142
	ds_read_b128 v[190:193], v69
	ds_read_b128 v[194:197], v110
	ds_read_b128 v[198:201], v111
	ds_read_b128 v[208:211], v112
	ds_read_b128 v[212:215], v113 offset:8192
	ds_read_b128 v[222:225], v118 offset:8192
	ds_read_b128 v[226:229], v69 offset:4096
	ds_read_b128 v[230:233], v110 offset:4096
	ds_read_b128 v[234:237], v111 offset:4096
	ds_read_b128 v[238:241], v112 offset:4096
	ds_read_b128 v[242:245], v113 offset:10240
	ds_read_b128 v[246:249], v118 offset:10240
	s_waitcnt lgkmcnt(11)
	v_mfma_f32_32x32x16_bf16 v[48:63], v[190:193], v[82:85], v[16:31]
	s_waitcnt lgkmcnt(10)
	v_mfma_f32_32x32x16_bf16 v[48:63], v[194:197], v[86:89], v[48:63]
	s_waitcnt lgkmcnt(9)
	v_mfma_f32_32x32x16_bf16 v[48:63], v[198:201], v[90:93], v[48:63]
	s_waitcnt lgkmcnt(8)
	v_mfma_f32_32x32x16_bf16 v[48:63], v[208:211], v[94:97], v[48:63]
	s_waitcnt lgkmcnt(7)
	v_mfma_f32_32x32x16_bf16 v[48:63], v[212:215], v[98:101], v[48:63]
	s_waitcnt lgkmcnt(6)
	v_mfma_f32_32x32x16_bf16 v[48:63], v[222:225], v[102:105], v[48:63]
	s_waitcnt lgkmcnt(5)
	v_mfma_f32_32x32x16_bf16 v[64:79], v[226:229], v[82:85], v[16:31]
	s_waitcnt lgkmcnt(4)
	v_mfma_f32_32x32x16_bf16 v[64:79], v[230:233], v[86:89], v[64:79]
	ds_read_b64_tr_b16 v[118:119], v143 offset:12288
	ds_read_b64_tr_b16 v[120:121], v143 offset:12800
	ds_read_b64_tr_b16 v[110:111], v143 offset:13312
	ds_read_b64_tr_b16 v[112:113], v143 offset:13824
	s_waitcnt lgkmcnt(7)
	v_mfma_f32_32x32x16_bf16 v[64:79], v[234:237], v[90:93], v[64:79]
	s_waitcnt lgkmcnt(6)
	v_mfma_f32_32x32x16_bf16 v[64:79], v[238:241], v[94:97], v[64:79]
	v_max_f32_e32 v106, v49, v49
	v_max_f32_e32 v107, v48, v48
	v_max_f32_e32 v106, v107, v106
	v_max3_f32 v106, v106, v50, v51
	v_max3_f32 v106, v106, v52, v53
	v_max3_f32 v106, v106, v54, v55
	v_max3_f32 v106, v106, v56, v57
	s_waitcnt lgkmcnt(5)
	v_mfma_f32_32x32x16_bf16 v[64:79], v[242:245], v[98:101], v[64:79]
	v_max3_f32 v106, v106, v58, v59
	v_max3_f32 v106, v106, v60, v61
	v_max3_f32 v106, v106, v62, v63
	s_waitcnt lgkmcnt(4)
	v_mfma_f32_32x32x16_bf16 v[64:79], v[246:249], v[102:105], v[64:79]
	s_nop 11
	v_max3_f32 v106, v106, v64, v65
	v_max3_f32 v106, v106, v66, v67
	v_max3_f32 v106, v106, v68, v69
	v_max3_f32 v106, v106, v70, v71
	v_max3_f32 v106, v106, v72, v73
	v_max3_f32 v106, v106, v74, v75
	v_max3_f32 v106, v106, v76, v77
	v_max3_f32 v144, v106, v78, v79
	ds_bpermute_b32 v145, v219, v144
	ds_read_b64_tr_b16 v[114:115], v143 offset:14336
	ds_read_b64_tr_b16 v[116:117], v143 offset:14848
	ds_read_b64_tr_b16 v[106:107], v143 offset:15360
	ds_read_b64_tr_b16 v[108:109], v143 offset:15872
	s_waitcnt lgkmcnt(4)
	ds_read_b64_tr_b16 v[190:191], v143 offset:16384
	ds_read_b64_tr_b16 v[192:193], v143 offset:16896
	ds_read_b64_tr_b16 v[194:195], v143 offset:17408
	ds_read_b64_tr_b16 v[196:197], v143 offset:17920
	ds_read_b64_tr_b16 v[198:199], v143 offset:18432
	ds_read_b64_tr_b16 v[200:201], v143 offset:18944
	ds_read_b64_tr_b16 v[208:209], v143 offset:19456
	ds_read_b64_tr_b16 v[210:211], v143 offset:19968
	v_max_f32_e32 v145, v145, v145
	v_max_f32_e32 v144, v144, v145
	v_cmp_lt_f32_e32 vcc, s72, v144
	s_cbranch_vccz .LBB0_349
	v_max_f32_e32 v16, v144, v144
	v_max_f32_e32 v16, 0, v16
	v_exp_f32_e64 v17, -v16
	s_and_saveexec_b64 s[28:29], s[40:41]
	ds_write_b32 v134, v17
	s_or_b64 exec, exec, s[28:29]
	s_waitcnt lgkmcnt(0)
	ds_read_b128 v[18:21], v135
	ds_read_b128 v[22:25], v135 offset:32
	ds_read_b128 v[26:29], v135 offset:64
	ds_read_b128 v[144:147], v135 offset:96
	v_pk_add_f32 v[48:49], v[48:49], v[16:17] op_sel_hi:[1,0] neg_lo:[0,1] neg_hi:[0,1]
	v_pk_add_f32 v[64:65], v[64:65], v[16:17] op_sel_hi:[1,0] neg_lo:[0,1] neg_hi:[0,1]
	v_pk_add_f32 v[50:51], v[50:51], v[16:17] op_sel_hi:[1,0] neg_lo:[0,1] neg_hi:[0,1]
	v_pk_add_f32 v[66:67], v[66:67], v[16:17] op_sel_hi:[1,0] neg_lo:[0,1] neg_hi:[0,1]
	v_pk_add_f32 v[52:53], v[52:53], v[16:17] op_sel_hi:[1,0] neg_lo:[0,1] neg_hi:[0,1]
	v_pk_add_f32 v[68:69], v[68:69], v[16:17] op_sel_hi:[1,0] neg_lo:[0,1] neg_hi:[0,1]
	v_pk_add_f32 v[54:55], v[54:55], v[16:17] op_sel_hi:[1,0] neg_lo:[0,1] neg_hi:[0,1]
	v_pk_add_f32 v[70:71], v[70:71], v[16:17] op_sel_hi:[1,0] neg_lo:[0,1] neg_hi:[0,1]
	v_pk_add_f32 v[56:57], v[56:57], v[16:17] op_sel_hi:[1,0] neg_lo:[0,1] neg_hi:[0,1]
	v_pk_add_f32 v[72:73], v[72:73], v[16:17] op_sel_hi:[1,0] neg_lo:[0,1] neg_hi:[0,1]
	v_pk_add_f32 v[58:59], v[58:59], v[16:17] op_sel_hi:[1,0] neg_lo:[0,1] neg_hi:[0,1]
	v_pk_add_f32 v[74:75], v[74:75], v[16:17] op_sel_hi:[1,0] neg_lo:[0,1] neg_hi:[0,1]
	v_pk_add_f32 v[60:61], v[60:61], v[16:17] op_sel_hi:[1,0] neg_lo:[0,1] neg_hi:[0,1]
	v_pk_add_f32 v[76:77], v[76:77], v[16:17] op_sel_hi:[1,0] neg_lo:[0,1] neg_hi:[0,1]
	v_pk_add_f32 v[62:63], v[62:63], v[16:17] op_sel_hi:[1,0] neg_lo:[0,1] neg_hi:[0,1]
	v_pk_add_f32 v[78:79], v[78:79], v[16:17] op_sel_hi:[1,0] neg_lo:[0,1] neg_hi:[0,1]
	v_pk_add_f32 v[152:153], v[122:123], v[16:17]
	v_pk_mul_f32 v[16:17], v[122:123], v[16:17]
	s_waitcnt lgkmcnt(3)
	v_pk_mul_f32 v[0:1], v[0:1], v[18:19]
	v_mov_b32_e32 v153, v17
	v_pk_add_f32 v[30:31], v[152:153], 0 neg_lo:[1,1] neg_hi:[1,1]
	v_pk_mul_f32 v[2:3], v[2:3], v[20:21]
	s_waitcnt lgkmcnt(2)
	v_pk_mul_f32 v[4:5], v[4:5], v[22:23]
	v_pk_mul_f32 v[6:7], v[6:7], v[24:25]
	s_waitcnt lgkmcnt(1)
	v_pk_mul_f32 v[8:9], v[8:9], v[26:27]
	v_pk_mul_f32 v[10:11], v[10:11], v[28:29]
	s_waitcnt lgkmcnt(0)
	v_pk_mul_f32 v[12:13], v[12:13], v[144:145]
	v_pk_mul_f32 v[14:15], v[14:15], v[146:147]
	v_pk_mul_f32 v[46:47], v[46:47], v[146:147]
	v_pk_mul_f32 v[42:43], v[42:43], v[28:29]
	v_pk_mul_f32 v[38:39], v[38:39], v[24:25]
	v_pk_mul_f32 v[34:35], v[34:35], v[20:21]
	v_pk_mul_f32 v[44:45], v[44:45], v[144:145]
	v_pk_mul_f32 v[40:41], v[40:41], v[26:27]
	v_pk_mul_f32 v[36:37], v[36:37], v[22:23]
	v_pk_mul_f32 v[32:33], v[32:33], v[18:19]
	v_mov_b32_e32 v31, v30
	v_mov_b32_e32 v29, v30
	v_mov_b32_e32 v28, v30
	v_mov_b32_e32 v27, v30
	v_mov_b32_e32 v26, v30
	v_mov_b32_e32 v25, v30
	v_mov_b32_e32 v24, v30
	v_mov_b32_e32 v23, v30
	v_mov_b32_e32 v22, v30
	v_mov_b32_e32 v21, v30
	v_mov_b32_e32 v20, v30
	v_mov_b32_e32 v19, v30
	v_mov_b32_e32 v18, v30
	v_mov_b32_e32 v17, v30
	v_mov_b32_e32 v16, v30
	v_mov_b64_e32 v[122:123], v[152:153]

.LBB0_351:
	v_exp_f32_e32 v48, v48
	v_exp_f32_e32 v64, v64
	v_exp_f32_e32 v49, v49
	v_exp_f32_e32 v65, v65
	v_exp_f32_e32 v50, v50
	v_exp_f32_e32 v66, v66
	v_exp_f32_e32 v51, v51
	v_exp_f32_e32 v67, v67
	v_add_f32_e32 v144, v64, v48
	v_exp_f32_e32 v52, v52
	v_exp_f32_e32 v68, v68
	v_add_f32_e32 v144, 0, v144
	v_add_f32_e32 v145, v65, v49
	v_exp_f32_e32 v53, v53
	v_exp_f32_e32 v69, v69
	v_add_f32_e32 v144, v145, v144
	v_add_f32_e32 v145, v66, v50
	v_exp_f32_e32 v54, v54
	v_exp_f32_e32 v70, v70
	v_add_f32_e32 v144, v145, v144
	v_add_f32_e32 v145, v67, v51
	v_exp_f32_e32 v55, v55
	v_exp_f32_e32 v71, v71
	v_add_f32_e32 v144, v145, v144
	v_add_f32_e32 v145, v68, v52
	v_exp_f32_e32 v56, v56
	v_exp_f32_e32 v72, v72
	v_add_f32_e32 v144, v145, v144
	v_add_f32_e32 v145, v69, v53
	v_exp_f32_e32 v57, v57
	v_exp_f32_e32 v73, v73
	v_add_f32_e32 v144, v145, v144
	v_add_f32_e32 v145, v70, v54
	v_exp_f32_e32 v58, v58
	v_exp_f32_e32 v74, v74
	v_add_f32_e32 v144, v145, v144
	v_add_f32_e32 v145, v71, v55
	v_exp_f32_e32 v59, v59
	v_exp_f32_e32 v75, v75
	v_add_f32_e32 v144, v145, v144
	v_add_f32_e32 v145, v72, v56
	v_add_f32_e32 v144, v145, v144
	v_add_f32_e32 v145, v73, v57
	v_add_f32_e32 v144, v145, v144
	v_add_f32_e32 v145, v74, v58
	v_add_f32_e32 v144, v145, v144
	v_add_f32_e32 v145, v75, v59
	v_add_f32_e32 v144, v145, v144
	v_exp_f32_e32 v145, v60
	v_exp_f32_e32 v76, v76
	v_exp_f32_e32 v77, v77
	v_exp_f32_e32 v146, v62
	v_exp_f32_e32 v78, v78
	v_add_f32_e32 v60, v76, v145
	v_add_f32_e32 v60, v60, v144
	v_exp_f32_e32 v144, v61
	v_exp_f32_e32 v147, v63
	v_exp_f32_e32 v79, v79
	v_cvt_pk_bf16_f32 v62, v52, v53
	v_add_f32_e32 v61, v77, v144
	v_add_f32_e32 v60, v61, v60
	v_add_f32_e32 v61, v78, v146
	v_add_f32_e32 v60, v61, v60
	v_add_f32_e32 v61, v79, v147
	v_add_f32_e32 v60, v61, v60
	v_add_f32_e32 v123, v123, v60
	v_cvt_pk_bf16_f32 v60, v48, v49
	v_cvt_pk_bf16_f32 v61, v50, v51
	v_cvt_pk_bf16_f32 v63, v54, v55
	v_cvt_pk_bf16_f32 v52, v64, v65
	v_cvt_pk_bf16_f32 v53, v66, v67
	v_cvt_pk_bf16_f32 v54, v68, v69
	v_cvt_pk_bf16_f32 v55, v70, v71
	v_cvt_pk_bf16_f32 v48, v72, v73
	v_cvt_pk_bf16_f32 v49, v74, v75
	v_cvt_pk_bf16_f32 v50, v76, v77
	v_cvt_pk_bf16_f32 v51, v78, v79
	s_waitcnt lgkmcnt(0)
	v_mfma_f32_32x32x16_bf16 v[0:15], v[60:63], v[118:121], v[0:15]
	v_cvt_pk_bf16_f32 v56, v56, v57
	v_cvt_pk_bf16_f32 v57, v58, v59
	v_cvt_pk_bf16_f32 v58, v145, v144
	v_cvt_pk_bf16_f32 v59, v146, v147
	s_add_i32 s0, s11, 1
	s_cmp_lg_u32 s11, 2
	v_mfma_f32_32x32x16_bf16 v[32:47], v[60:63], v[190:193], v[32:47]
	s_cselect_b32 s11, s0, 0
	s_mov_b64 s[0:1], 0x18000
	v_lshl_add_u64 v[124:125], v[124:125], 0, s[82:83]
	v_lshl_add_u64 v[126:127], v[126:127], 0, s[0:1]
	s_mov_b64 s[70:71], 0x18000
	v_lshl_add_u64 v[128:129], v[128:129], 0, s[0:1]
	s_cmp_eq_u32 s36, s37
	v_mfma_f32_32x32x16_bf16 v[0:15], v[56:59], v[110:113], v[0:15]
	v_mfma_f32_32x32x16_bf16 v[32:47], v[56:59], v[194:197], v[32:47]
	v_mfma_f32_32x32x16_bf16 v[0:15], v[52:55], v[114:117], v[0:15]
	v_mfma_f32_32x32x16_bf16 v[32:47], v[52:55], v[198:201], v[32:47]
	v_mfma_f32_32x32x16_bf16 v[0:15], v[48:51], v[106:109], v[0:15]
	v_mfma_f32_32x32x16_bf16 v[32:47], v[48:51], v[208:211], v[32:47]
	s_cbranch_scc0 .LBB0_341
	ds_bpermute_b32 v16, v219, v123
	s_nop 0
	v_cmp_eq_u32_e32 vcc, 0, v130
	s_and_saveexec_b64 s[28:29], vcc
	s_cbranch_execz .LBB0_354
	s_waitcnt lgkmcnt(0)
	v_add_f32_e32 v16, v123, v16
	v_div_scale_f32 v17, s[34:35], v16, v16, 1.0
	v_rcp_f32_e32 v18, v17
	v_div_scale_f32 v19, vcc, 1.0, v16, 1.0
	v_fma_f32 v20, -v17, v18, 1.0
	v_fmac_f32_e32 v18, v20, v18
	v_mul_f32_e32 v20, v19, v18
	v_fma_f32 v21, -v17, v20, v19
	v_fmac_f32_e32 v20, v21, v18
	v_fma_f32 v17, -v17, v20, v19
	v_div_fmas_f32 v17, v17, v18, v20
	v_div_fixup_f32 v16, v17, v16, 1.0
	v_lshl_add_u32 v17, v131, 2, s6
	ds_write_b32 v17, v16
